# swiglu units: epilogues of the two wave halves no longer aligned by an extra barrier (each half's epilogue overlaps the other half's MFMA cluster); only the last unit re-aligns
# baseline (speedup 1.0000x reference)
.LBB7_355:
	s_add_u32 s0, s68, s14
	s_addc_u32 s1, s69, s15
	s_add_u32 s6, s85, s18
	s_addc_u32 s7, s31, s19
	s_andn2_b64 vcc, exec, s[54:55]
	s_cbranch_vccnz .LBB7_363
	s_and_b64 s[28:29], s[40:41], exec
	s_cselect_b32 s9, s1, s17
	s_cselect_b32 s13, s0, s16
	s_cselect_b32 s28, s7, s43
	s_cselect_b32 s39, s6, s42
	s_add_u32 s16, s16, 0x40080
	s_addc_u32 s17, s17, 0
	s_add_u32 s56, s42, 0x100
	s_addc_u32 s57, s43, 0
	s_mov_b32 s42, 0
	s_cmp_lt_u32 s22, 2
	s_cbranch_scc1 .Lswi_nobar
	s_andn2_b64 vcc, exec, s[50:51]
	s_cbranch_vccnz .Lswi_nobar
	s_nop 0

.Lswi_pref:
	v_lshlrev_b32_e32 v236, 6, v142
	v_add_u32_e32 v236, 0x20000, v236
	ds_read_b64 v[204:205], v236
	ds_read_b64 v[206:207], v236 offset:1024
	ds_read_b64 v[208:209], v236 offset:2048
	ds_read_b64 v[210:211], v236 offset:3072
	ds_read_b64 v[212:213], v236 offset:8192
	ds_read_b64 v[214:215], v236 offset:9216
	ds_read_b64 v[216:217], v236 offset:10240
	ds_read_b64 v[218:219], v236 offset:11264
	s_andn2_b64 vcc, s[52:53], s[40:41]
	s_and_b64 vcc, exec, vcc
	s_cbranch_vccz .LBB7_360
